# static s_setprio 1 for waves 0-3 at kernel entry (other half than previous); attention setprio flips deleted
# speedup vs baseline: 1.0038x; 1.0038x over previous
; #define LAS __attribute__((address_space(3)))
; __global__ void __launch_bounds__(512) fwd_megakernel(Params p) {
;   __shared__ __attribute__((aligned(1024))) char smem[155648];
;   cg::grid_group grid = cg::this_grid();
;   const int G = gridDim.x;
;   char* ws = p.ws;
;   unsigned* bar = (unsigned*)(ws + OFF_BAR);
;   volatile LAS unsigned* xst = (volatile LAS unsigned*)(smem + 155648 - 16);
;   if (threadIdx.x == 0) { xst[0] = 0u; xst[1] = 0u; }
;   const XcdBarrier xb = xcd_barrier_post(bar, xst);
_Z14fwd_megakernel6Params:
	s_load_dword s78, s[0:1], 0xc8
	s_load_dwordx2 s[96:97], s[0:1], 0xc0
	s_add_u32 s6, s0, 0xc8
	s_addc_u32 s7, s1, 0
	v_mov_b32_e32 v1, 0
	v_readfirstlane_b32 s10, v0
	s_nop 3
	s_and_b32 s10, s10, 0x3ff
	s_lshr_b32 s10, s10, 6
	s_cmp_lt_u32 s10, 4
	s_cbranch_scc0 .Lprio_done
	s_setprio 1
